# out_ln rendezvous: returning atomic add, the last of the 8 owners skips the counter poll
# speedup vs baseline: 1.0514x; 1.0006x over previous
.LBB0_132:
	s_or_b64 exec, exec, s[42:43]
	s_waitcnt vmcnt(0)
	v_cmp_eq_u32_e32 vcc, 0, v0
	s_barrier
	s_and_saveexec_b64 s[30:31], vcc
	s_cbranch_execz .LBB0_149
	s_mov_b64 s[46:47], exec
	s_lshl_b32 s42, s33, 2
	v_mbcnt_lo_u32_b32 v3, s46, 0
	s_add_u32 s42, s81, s42
	v_mbcnt_hi_u32_b32 v3, s47, v3
	s_mov_b32 s94, s92
	s_addc_u32 s43, s84, 0
	v_cmp_eq_u32_e32 vcc, 0, v3
	s_and_saveexec_b64 s[50:51], vcc
	s_cbranch_execz .LBB0_135
	s_bcnt1_i32_b64 s46, s[46:47]
	v_mov_b32_e32 v3, s46
	global_atomic_add v3, v145, v3, s[42:43] sc0
.LBB0_135:
	s_or_b64 exec, exec, s[50:51]
	s_mov_b32 s50, 0x1000000
	s_mov_b32 s93, 0x8000
	s_mov_b32 s92, s94
	s_waitcnt vmcnt(0)
	v_cmp_lt_u32_e32 vcc, 6, v3
	s_cbranch_vccnz .LBB0_148
	s_branch .LBB0_138

.LBB0_728:
	s_or_b64 exec, exec, s[44:45]
	s_waitcnt vmcnt(0)
	v_cmp_eq_u32_e32 vcc, 0, v0
	s_barrier
	s_and_saveexec_b64 s[44:45], vcc
	s_cbranch_execz .LBB0_745
	s_mov_b64 s[50:51], exec
	s_lshl_b32 s46, s33, 2
	v_readlane_b32 s47, v255, 12
	v_mbcnt_lo_u32_b32 v3, s50, 0
	s_add_u32 s46, s47, s46
	v_mbcnt_hi_u32_b32 v3, s51, v3
	s_addc_u32 s47, s91, 0
	v_cmp_eq_u32_e32 vcc, 0, v3
	s_and_saveexec_b64 s[58:59], vcc
	s_cbranch_execz .LBB0_731
	s_bcnt1_i32_b64 s50, s[50:51]
	v_mov_b32_e32 v3, s50
	global_atomic_add v3, v145, v3, s[46:47] sc0
.LBB0_731:
	s_or_b64 exec, exec, s[58:59]
	s_mov_b32 s58, 0x1000000
	s_waitcnt vmcnt(0)
	v_cmp_lt_u32_e32 vcc, 6, v3
	s_cbranch_vccnz .LBB0_744
	s_branch .LBB0_734

.LBB0_1052:
	s_or_b64 exec, exec, s[42:43]
	s_waitcnt vmcnt(0)
	v_cmp_eq_u32_e32 vcc, 0, v0
	s_barrier
	s_and_saveexec_b64 s[30:31], vcc
	s_cbranch_execz .LBB0_1069
	s_mov_b64 s[46:47], exec
	s_lshl_b32 s42, s33, 2
	v_mbcnt_lo_u32_b32 v3, s46, 0
	s_add_u32 s42, s81, s42
	v_mbcnt_hi_u32_b32 v3, s47, v3
	s_addc_u32 s43, s84, 0
	v_cmp_eq_u32_e32 vcc, 0, v3
	s_and_saveexec_b64 s[50:51], vcc
	s_cbranch_execz .LBB0_1055
	s_bcnt1_i32_b64 s46, s[46:47]
	v_mov_b32_e32 v3, s46
	global_atomic_add v3, v145, v3, s[42:43] sc0
.LBB0_1055:
	s_or_b64 exec, exec, s[50:51]
	s_mov_b32 s50, 0x1000000
	s_waitcnt vmcnt(0)
	v_cmp_lt_u32_e32 vcc, 6, v3
	s_cbranch_vccnz .LBB0_1068
	s_branch .LBB0_1058
